# NSA work tickets prefetched one tile ahead (atomic issued at tile start, value parked in LDS mid-tile)
# baseline (speedup 1.0000x reference)
.LBB0_1464:
	s_or_b64 exec, exec, s[0:1]
	s_andn2_b64 vcc, exec, s[18:19]
	s_waitcnt lgkmcnt(0)
	s_barrier
	s_cbranch_vccnz .LBB0_1682
	s_add_u32 s100, s72, 0x2f80000
	s_addc_u32 s101, s73, 0
	s_mov_b32 s98, 0x2000
	s_mov_b32 s99, 0
	v_lshrrev_b32_e32 v244, 4, v220
	v_and_b32_e32 v245, 3, v244
	v_lshrrev_b32_e32 v246, 7, v220
	v_lshl_or_b32 v245, v246, 2, v245
	v_and_b32_e32 v246, 15, v220
	v_xor_b32_e32 v245, v245, v246
	v_lshlrev_b32_e32 v245, 4, v245
	v_lshl_or_b32 v249, v244, 8, v245
	v_xor_b32_e32 v250, 0x80, v249
	v_and_b32_e32 v245, 7, v244
	v_and_b32_e32 v246, 7, v220
	v_xor_b32_e32 v245, v245, v246
	v_lshlrev_b32_e32 v245, 4, v245
	v_lshrrev_b32_e32 v246, 3, v220
	v_lshl_or_b32 v251, v246, 7, v245
	v_lshlrev_b32_e32 v252, 4, v220
	v_add_u32_e32 v252, 0x1000, v252
	v_mov_b32_e32 v253, 0
	s_mov_b32 s57, 0
	s_cmpk_lg_i32 s74, 0x200
	s_mov_b32 s3, s57
	s_cselect_b64 s[52:53], -1, 0
	s_lshr_b32 s0, s2, 8
	s_lshl_b64 s[58:59], s[2:3], 8
	s_add_u32 s60, s72, 0x13200000
	s_addc_u32 s61, s73, 0
	s_add_u32 s62, s72, 0x3000000
	s_addc_u32 s63, s73, 0
	s_add_u32 s3, s72, 0x3600000
	s_addc_u32 s87, s73, 0
	s_add_u32 s88, s72, 0x3800000
	s_addc_u32 s89, s73, 0
	s_add_u32 s64, s72, 0x7200000
	s_addc_u32 s65, s73, 0
	s_add_u32 s90, s72, 0xb200000
	s_addc_u32 s91, s73, 0
	v_writelane_b32 v254, s54, 32
	s_add_u32 s92, s72, 0xd200000
	s_addc_u32 s93, s73, 0
	v_writelane_b32 v254, s55, 33
	v_writelane_b32 v254, s0, 24
	s_add_u32 s0, s72, 0x11200000
	v_writelane_b32 v254, s0, 22
	s_addc_u32 s0, s73, 0
	s_add_u32 s96, s72, 0xf200000
	s_addc_u32 s97, s73, 0
	s_movk_i32 s4, 0x1ff
	s_waitcnt vmcnt(15)
	v_mov_b32_e32 v168, 0x10200
	v_mov_b32_e32 v17, 0
	s_mov_b32 s5, 0x8000
	s_movk_i32 s8, 0x400
	s_movk_i32 s9, 0x7fff
	v_mov_b32_e32 v169, 0xf149f2ca
	v_mbcnt_hi_u32_b32 v170, -1, v221
	v_mov_b32_e32 v171, 0xc0
	v_mov_b32_e32 v172, 0x7149f200
	v_mov_b32_e32 v173, 0x7149f2ca
	v_mov_b32_e32 v174, 1
	s_mov_b32 s6, s2
	v_writelane_b32 v254, s0, 26
	v_cmp_eq_u32_e32 vcc, 0, v220
	s_and_saveexec_b64 s[0:1], vcc
	s_cbranch_execz .Lnsa_tk1
	s_and_b32 s7, s2, 7
	s_lshl_b32 s7, s7, 6
	v_mov_b32_e32 v2, s7
	v_mov_b32_e32 v1, 1
	global_atomic_add v1, v2, v1, s[100:101] sc0
	s_waitcnt vmcnt(0)
	v_mov_b32_e32 v2, 0x10608
	ds_write_b32 v2, v1
	s_waitcnt lgkmcnt(0)
.Lnsa_tk1:
	s_or_b64 exec, exec, s[0:1]
	s_branch .LBB0_1468

.LBB0_1468:
	v_mov_b32_e32 v0, v220
	s_barrier
	v_mov_b32_e32 v1, 0x10608
	ds_read_b32 v1, v1
	s_waitcnt lgkmcnt(0)
	s_nop 1
	v_readfirstlane_b32 s6, v1
	s_nop 3
	s_cmp_gt_u32 s6, 0x1ff
	s_cbranch_scc1 .LBB0_1681
	s_sub_i32 s50, 0x1ff, s6
	s_and_b32 s66, s2, 7
	v_cmp_eq_u32_e32 vcc, 0, v220
	s_and_saveexec_b64 s[0:1], vcc
	s_cbranch_execz .Lnsa_tk2
	s_lshl_b32 s7, s66, 6
	v_mov_b32_e32 v2, s7
	v_mov_b32_e32 v255, 1
	global_atomic_add v255, v2, v255, s[100:101] sc0
.Lnsa_tk2:
	s_or_b64 exec, exec, s[0:1]
.LBB0_1472:
	s_waitcnt vmcnt(10)
	v_and_b32_e32 v157, 63, v0
	v_ashrrev_i32_e32 v1, 6, v0
	s_movk_i32 s0, 0x2080
	v_lshl_add_u32 v2, v0, 2, v168
	v_mul_lo_u32 v158, v1, s0
	ds_write_b32 v2, v17
	v_lshlrev_b32_e32 v2, 2, v157
	v_add3_u32 v2, v158, v2, s5
	v_or_b32_e32 v3, 0xffffffc0, v157
	s_mov_b64 s[0:1], 0

.LBB0_1656:
	v_mov_b32_e32 v4, v220
	s_lshl_b64 s[0:1], s[66:67], 21
	v_ashrrev_i32_e32 v0, 6, v4
	s_waitcnt lgkmcnt(0)
	v_lshl_add_u32 v2, v0, 3, s76
	v_lshrrev_b32_e32 v3, 2, v4
	v_and_or_b32 v2, v3, 3, v2
	v_and_or_b32 v1, v4, 3, s7
	v_mul_lo_u32 v2, v2, 48
	s_waitcnt vmcnt(0)
	v_cmp_eq_u32_e32 vcc, 0, v220
	s_and_saveexec_b64 s[20:21], vcc
	v_mov_b32_e32 v243, 0x10608
	ds_write_b32 v243, v255
	s_or_b64 exec, exec, s[20:21]
	v_mad_u32_u24 v14, v1, 3, v2
	v_ashrrev_i32_e32 v15, 31, v14
	v_lshl_add_u64 v[2:3], v[14:15], 2, s[62:63]
	global_load_dword v16, v[2:3], off offset:4
	v_ashrrev_i32_e32 v1, 31, v0
	v_lshlrev_b64 v[0:1], 6, v[0:1]
	v_lshl_add_u64 v[0:1], v[0:1], 0, s[58:59]
	v_and_or_b32 v0, v4, 63, v0
	v_lshlrev_b64 v[0:1], 8, v[0:1]
	v_lshl_add_u64 v[0:1], s[64:65], 0, v[0:1]
	global_load_dwordx4 v[2:5], v[0:1], off
	global_load_dwordx4 v[6:9], v[0:1], off offset:16
	global_load_dwordx4 v[10:13], v[0:1], off offset:32
	global_load_dwordx4 v[116:119], v[0:1], off offset:48
	global_load_dwordx4 v[120:123], v[0:1], off offset:64
	global_load_dwordx4 v[124:127], v[0:1], off offset:80
	global_load_dwordx4 v[128:131], v[0:1], off offset:96
	global_load_dwordx4 v[132:135], v[0:1], off offset:112
	v_mov_b32_e32 v15, v176
	s_nop 1
	v_permlane32_swap_b32_e32 v176, v15
	v_add_f32_e32 v15, v176, v15
	v_mov_b32_e32 v18, v15
	s_nop 1
	v_permlane16_swap_b32_e32 v15, v18
	v_add_f32_e32 v18, v15, v18
	v_add_u32_e32 v14, 0xc0, v14
	v_ashrrev_i32_e32 v15, 31, v14
	v_lshl_add_u64 v[14:15], v[14:15], 2, s[62:63]
	s_waitcnt vmcnt(8)
	v_div_scale_f32 v19, s[10:11], v18, v18, v16
	v_rcp_f32_e32 v136, v19
	v_div_scale_f32 v137, vcc, v16, v18, v16
	s_max_i32 s10, s77, 0x1ff
	v_fma_f32 v138, -v19, v136, 1.0
	v_fmac_f32_e32 v136, v138, v136
	v_mul_f32_e32 v138, v137, v136
	v_fma_f32 v139, -v19, v138, v137
	v_fmac_f32_e32 v138, v139, v136
	v_fma_f32 v19, -v19, v138, v137
	v_div_fmas_f32 v19, v19, v136, v138
	v_div_fixup_f32 v16, v19, v18, v16
	s_waitcnt vmcnt(7)
	v_pk_fma_f32 v[4:5], v[114:115], v[16:17], v[4:5] op_sel_hi:[1,0,1]
	v_pk_fma_f32 v[2:3], v[112:113], v[16:17], v[2:3] op_sel_hi:[1,0,1]
	s_waitcnt vmcnt(6)
	v_pk_fma_f32 v[8:9], v[110:111], v[16:17], v[8:9] op_sel_hi:[1,0,1]
	v_pk_fma_f32 v[6:7], v[108:109], v[16:17], v[6:7] op_sel_hi:[1,0,1]
	s_waitcnt vmcnt(5)
	v_pk_fma_f32 v[12:13], v[106:107], v[16:17], v[12:13] op_sel_hi:[1,0,1]
	v_pk_fma_f32 v[10:11], v[104:105], v[16:17], v[10:11] op_sel_hi:[1,0,1]
	s_waitcnt vmcnt(4)
	v_pk_fma_f32 v[102:103], v[102:103], v[16:17], v[118:119] op_sel_hi:[1,0,1]
	v_pk_fma_f32 v[100:101], v[100:101], v[16:17], v[116:117] op_sel_hi:[1,0,1]
	s_waitcnt vmcnt(3)
	v_pk_fma_f32 v[98:99], v[98:99], v[16:17], v[122:123] op_sel_hi:[1,0,1]
	v_pk_fma_f32 v[96:97], v[96:97], v[16:17], v[120:121] op_sel_hi:[1,0,1]
	s_waitcnt vmcnt(2)
	v_pk_fma_f32 v[94:95], v[94:95], v[16:17], v[126:127] op_sel_hi:[1,0,1]
	v_pk_fma_f32 v[92:93], v[92:93], v[16:17], v[124:125] op_sel_hi:[1,0,1]
	s_waitcnt vmcnt(1)
	v_pk_fma_f32 v[90:91], v[90:91], v[16:17], v[130:131] op_sel_hi:[1,0,1]
	v_pk_fma_f32 v[88:89], v[88:89], v[16:17], v[128:129] op_sel_hi:[1,0,1]
	s_waitcnt vmcnt(0)
	v_pk_fma_f32 v[86:87], v[86:87], v[16:17], v[134:135] op_sel_hi:[1,0,1]
	v_pk_fma_f32 v[84:85], v[84:85], v[16:17], v[132:133] op_sel_hi:[1,0,1]
	global_store_dwordx4 v[0:1], v[2:5], off
	global_store_dwordx4 v[0:1], v[6:9], off offset:16
	global_store_dwordx4 v[0:1], v[10:13], off offset:32
	global_store_dwordx4 v[0:1], v[100:103], off offset:48
	global_store_dwordx4 v[0:1], v[96:99], off offset:64
	global_store_dwordx4 v[0:1], v[92:95], off offset:80
	global_store_dwordx4 v[0:1], v[88:91], off offset:96
	global_store_dwordx4 v[0:1], v[84:87], off offset:112
	global_load_dword v3, v[14:15], off offset:4
	global_load_dwordx4 v[4:7], v[0:1], off offset:128
	global_load_dwordx4 v[8:11], v[0:1], off offset:144
	s_nop 0
	global_load_dwordx4 v[12:15], v[0:1], off offset:160
	global_load_dwordx4 v[84:87], v[0:1], off offset:176
	global_load_dwordx4 v[88:91], v[0:1], off offset:192
	global_load_dwordx4 v[92:95], v[0:1], off offset:208
	global_load_dwordx4 v[96:99], v[0:1], off offset:224
	global_load_dwordx4 v[100:103], v[0:1], off offset:240
	v_mov_b32_e32 v16, v175
	s_nop 1
	v_permlane32_swap_b32_e32 v175, v16
	v_add_f32_e32 v16, v175, v16
	v_mov_b32_e32 v18, v16
	s_nop 1
	v_permlane16_swap_b32_e32 v16, v18
	v_add_f32_e32 v16, v16, v18
	s_addk_i32 s10, 0xfe01
	s_lshr_b32 s10, s10, 6
	v_mov_b32_e32 v2, v220
	s_cmp_gt_i32 s10, s86
	s_waitcnt vmcnt(8)
	v_div_scale_f32 v18, s[12:13], v16, v16, v3
	v_rcp_f32_e32 v19, v18
	v_div_scale_f32 v104, vcc, v3, v16, v3
	v_fma_f32 v105, -v18, v19, 1.0
	v_fmac_f32_e32 v19, v105, v19
	v_mul_f32_e32 v105, v104, v19
	v_fma_f32 v106, -v18, v105, v104
	v_fmac_f32_e32 v105, v106, v19
	v_fma_f32 v18, -v18, v105, v104
	v_div_fmas_f32 v18, v18, v19, v105
	v_div_fixup_f32 v16, v18, v16, v3
	s_waitcnt vmcnt(7)
	v_pk_fma_f32 v[6:7], v[82:83], v[16:17], v[6:7] op_sel_hi:[1,0,1]
	v_pk_fma_f32 v[4:5], v[80:81], v[16:17], v[4:5] op_sel_hi:[1,0,1]
	s_waitcnt vmcnt(6)
	v_pk_fma_f32 v[10:11], v[78:79], v[16:17], v[10:11] op_sel_hi:[1,0,1]
	v_pk_fma_f32 v[8:9], v[76:77], v[16:17], v[8:9] op_sel_hi:[1,0,1]
	s_waitcnt vmcnt(5)
	v_pk_fma_f32 v[14:15], v[74:75], v[16:17], v[14:15] op_sel_hi:[1,0,1]
	v_pk_fma_f32 v[12:13], v[72:73], v[16:17], v[12:13] op_sel_hi:[1,0,1]
	s_waitcnt vmcnt(4)
	v_pk_fma_f32 v[70:71], v[70:71], v[16:17], v[86:87] op_sel_hi:[1,0,1]
	v_pk_fma_f32 v[68:69], v[68:69], v[16:17], v[84:85] op_sel_hi:[1,0,1]
	s_waitcnt vmcnt(3)
	v_pk_fma_f32 v[64:65], v[64:65], v[16:17], v[88:89] op_sel_hi:[1,0,1]
	v_pk_fma_f32 v[66:67], v[66:67], v[16:17], v[90:91] op_sel_hi:[1,0,1]
	s_waitcnt vmcnt(2)
	v_pk_fma_f32 v[60:61], v[60:61], v[16:17], v[92:93] op_sel_hi:[1,0,1]
	v_pk_fma_f32 v[62:63], v[62:63], v[16:17], v[94:95] op_sel_hi:[1,0,1]
	s_waitcnt vmcnt(1)
	v_pk_fma_f32 v[56:57], v[56:57], v[16:17], v[96:97] op_sel_hi:[1,0,1]
	v_pk_fma_f32 v[58:59], v[58:59], v[16:17], v[98:99] op_sel_hi:[1,0,1]
	s_waitcnt vmcnt(0)
	v_pk_fma_f32 v[52:53], v[52:53], v[16:17], v[100:101] op_sel_hi:[1,0,1]
	v_pk_fma_f32 v[54:55], v[54:55], v[16:17], v[102:103] op_sel_hi:[1,0,1]
	global_store_dwordx4 v[0:1], v[4:7], off offset:128
	global_store_dwordx4 v[0:1], v[8:11], off offset:144
	global_store_dwordx4 v[0:1], v[12:15], off offset:160
	global_store_dwordx4 v[0:1], v[68:71], off offset:176
	global_store_dwordx4 v[0:1], v[64:67], off offset:192
	global_store_dwordx4 v[0:1], v[60:63], off offset:208
	global_store_dwordx4 v[0:1], v[56:59], off offset:224
	global_store_dwordx4 v[0:1], v[52:55], off offset:240
	s_cbranch_scc1 .LBB0_1466
	s_lshl_b64 s[12:13], s[0:1], 1
	v_readlane_b32 s0, v254, 22
	s_add_u32 s0, s0, s12
	v_readlane_b32 s1, v254, 26
	s_addc_u32 s1, s1, s13
	s_add_u32 s12, s96, s12
	v_lshrrev_b32_e32 v0, 3, v2
	s_mov_b32 s11, s57
	s_addc_u32 s13, s97, s13
	v_ashrrev_i32_e32 v6, 2, v2
	v_and_b32_e32 v0, 12, v0
	s_lshl_b64 s[14:15], s[10:11], 14
	v_and_or_b32 v7, v6, 3, v0
	s_add_u32 s16, s12, s14
	v_lshlrev_b32_e32 v0, 5, v2
	s_addc_u32 s17, s13, s15
	v_ashrrev_i32_e32 v1, 31, v0
	v_mov_b64_e32 v[0:1], v[252:253]
	s_add_u32 s14, s0, s14
	s_addc_u32 s15, s1, s15
	v_lshlrev_b32_e32 v5, 2, v2
	v_lshlrev_b32_e32 v4, 4, v6
	v_and_b32_e32 v6, 12, v5
	v_bitop3_b32 v11, v7, v4, v6 bitop3:0xde
	v_lshlrev_b32_e32 v156, 4, v11
	v_or_b32_e32 v11, 1, v6
	v_bitop3_b32 v11, v11, v4, v7 bitop3:0xde
	v_lshlrev_b32_e32 v157, 4, v11
	v_or_b32_e32 v11, 2, v6
	v_or_b32_e32 v6, 3, v6
	v_bfe_u32 v3, v2, 2, 3
	v_bitop3_b32 v11, v11, v4, v7 bitop3:0xde
	v_bitop3_b32 v4, v6, v4, v7 bitop3:0xde
	v_lshlrev_b32_e32 v159, 4, v4
	v_and_b32_e32 v4, -8, v5
	v_and_b32_e32 v6, 4, v5
	v_bitop3_b32 v5, v5, v3, 4 bitop3:0x6c
	v_or_b32_e32 v5, v5, v4
	v_lshlrev_b32_e32 v160, 4, v5
	v_bitop3_b32 v5, v6, v3, 1 bitop3:0x36
	v_or_b32_e32 v5, v5, v4
	v_lshlrev_b32_e32 v161, 4, v5
	v_bitop3_b32 v5, v6, v3, 2 bitop3:0x36
	v_bitop3_b32 v3, v6, v3, 3 bitop3:0x36
	v_lshl_add_u64 v[152:153], s[12:13], 0, v[0:1]
	v_lshl_add_u64 v[154:155], s[0:1], 0, v[0:1]
	v_ashrrev_i32_e32 v0, 3, v2
	v_lshrrev_b32_e32 v8, 4, v2
	v_bfe_u32 v9, v2, 4, 2
	v_and_b32_e32 v10, 15, v2
	v_or_b32_e32 v5, v5, v4
	v_or_b32_e32 v3, v3, v4
	v_and_b32_e32 v0, -8, v0
	v_lshlrev_b32_e32 v162, 4, v5
	v_lshlrev_b32_e32 v163, 4, v3
	v_add_u32_e32 v164, s77, v0
	v_and_b32_e32 v0, 12, v2
	v_bitop3_b32 v1, v8, v10, 3 bitop3:0x6c
	v_bitop3_b32 v3, v9, v10, 4 bitop3:0x36
	v_bitop3_b32 v4, v9, v10, 8 bitop3:0x36
	v_bitop3_b32 v5, v9, v10, 12 bitop3:0x36
	v_add_lshl_u32 v0, v0, v10, 8
	v_lshlrev_b32_e32 v1, 4, v1
	v_lshlrev_b32_e32 v3, 4, v3
	v_lshlrev_b32_e32 v4, 4, v4
	v_lshlrev_b32_e32 v5, 4, v5
	v_or_b32_e32 v165, v1, v0
	v_or_b32_e32 v167, v3, v0
	v_or_b32_e32 v176, v4, v0
	v_or_b32_e32 v178, v5, v0
	v_or_b32_e32 v0, 0x2000, v0
	v_or3_b32 v180, v1, v0, s8
	v_or3_b32 v181, v3, v0, s8
	v_or3_b32 v182, v4, v0, s8
	v_or3_b32 v183, v5, v0, s8
	v_bfe_u32 v0, v2, 2, 2
	v_or_b32_e32 v185, v164, v0
	v_bfe_u32 v0, v2, 1, 3
	v_bitop3_b32 v1, v8, v0, 3 bitop3:0x6c
	v_bitop3_b32 v0, v9, v0, 4 bitop3:0x36
	v_mov_b32_e32 v18, v17
	v_mov_b32_e32 v19, v17
	v_lshlrev_b32_e32 v2, 7, v10
	v_lshlrev_b32_e32 v1, 4, v1
	v_lshlrev_b32_e32 v0, 4, v0
	v_mov_b32_e32 v16, v17
	v_mov_b64_e32 v[54:55], v[18:19]
	v_mov_b64_e32 v[58:59], v[18:19]
	v_mov_b64_e32 v[62:63], v[18:19]
	v_mov_b64_e32 v[66:67], v[18:19]
	v_mov_b64_e32 v[70:71], v[18:19]
	v_mov_b64_e32 v[74:75], v[18:19]
	v_mov_b64_e32 v[78:79], v[18:19]
	v_mov_b64_e32 v[82:83], v[18:19]
	v_mov_b64_e32 v[86:87], v[18:19]
	v_mov_b64_e32 v[90:91], v[18:19]
	v_mov_b64_e32 v[94:95], v[18:19]
	v_mov_b64_e32 v[98:99], v[18:19]
	v_mov_b64_e32 v[102:103], v[18:19]
	v_mov_b64_e32 v[106:107], v[18:19]
	v_mov_b64_e32 v[110:111], v[18:19]
	v_mov_b64_e32 v[114:115], v[18:19]
	v_lshlrev_b32_e32 v158, 4, v11
	v_or_b32_e32 v166, 0x400, v165
	v_or_b32_e32 v175, 0x400, v167
	v_or_b32_e32 v177, 0x400, v176
	v_or_b32_e32 v179, 0x400, v178
	v_add_u32_e32 v184, 0xfffffe03, v164
	v_add_u32_e32 v186, 0xfffffe00, v185
	v_lshlrev_b32_e32 v187, 3, v9
	v_add_u32_e32 v188, 0xfffffe07, v164
	v_or_b32_e32 v189, 4, v185
	v_add_u32_e32 v190, 0xfffffe04, v185
	s_lshl_b32 s11, s10, 6
	v_mov_b32_e32 v193, 0
	v_mov_b32_e32 v194, 0xf149f2ca
	v_add_u32_e32 v191, v2, v1
	v_add_u32_e32 v192, v2, v0
	v_mov_b64_e32 v[52:53], v[16:17]
	v_mov_b64_e32 v[56:57], v[16:17]
	v_mov_b64_e32 v[60:61], v[16:17]
	v_mov_b64_e32 v[64:65], v[16:17]
	v_mov_b64_e32 v[68:69], v[16:17]
	v_mov_b64_e32 v[72:73], v[16:17]
	v_mov_b64_e32 v[76:77], v[16:17]
	v_mov_b64_e32 v[80:81], v[16:17]
	v_mov_b64_e32 v[84:85], v[16:17]
	v_mov_b64_e32 v[88:89], v[16:17]
	v_mov_b64_e32 v[92:93], v[16:17]
	v_mov_b64_e32 v[96:97], v[16:17]
	v_mov_b64_e32 v[100:101], v[16:17]
	v_mov_b64_e32 v[104:105], v[16:17]
	v_mov_b64_e32 v[108:109], v[16:17]
	v_mov_b64_e32 v[112:113], v[16:17]
	v_mov_b32_e32 v16, 0xf149f2ca
	v_mov_b32_e32 v19, 0
	v_mov_b32_e32 v143, 0
	v_mov_b32_e32 v142, v249
	v_lshl_add_u64 v[116:117], s[12:13], 0, v[142:143]
	v_add_u32_e32 v142, 0x1000, v250
	v_lshl_add_u64 v[118:119], s[12:13], 0, v[142:143]
	v_add_u32_e32 v142, 0x2000, v249
	v_lshl_add_u64 v[120:121], s[12:13], 0, v[142:143]
	v_add_u32_e32 v142, 0x3000, v250
	v_lshl_add_u64 v[122:123], s[12:13], 0, v[142:143]
	v_mov_b32_e32 v142, v251
	v_lshl_add_u64 v[128:129], s[0:1], 0, v[142:143]
	v_add_u32_e32 v142, 0x1000, v251
	v_lshl_add_u64 v[130:131], s[0:1], 0, v[142:143]
	v_add_u32_e32 v142, 0x2000, v251
	v_lshl_add_u64 v[136:137], s[0:1], 0, v[142:143]
	v_add_u32_e32 v142, 0x3000, v251
	v_lshl_add_u64 v[138:139], s[0:1], 0, v[142:143]
	v_lshrrev_b32_e32 v143, 6, v220
	v_lshlrev_b32_e32 v143, 10, v143
	s_lshl_b32 s14, s10, 14
	s_mov_b32 s15, 0
	v_readfirstlane_b32 vcc_lo, v143
	s_mov_b32 m0, vcc_lo
	v_lshl_add_u64 v[140:141], v[116:117], 0, s[14:15]
	global_load_lds_dwordx4 v[140:141], off
	s_add_u32 m0, m0, 0x1000
	v_lshl_add_u64 v[140:141], v[118:119], 0, s[14:15]
	global_load_lds_dwordx4 v[140:141], off
	s_add_u32 m0, m0, 0x1000
	v_lshl_add_u64 v[140:141], v[120:121], 0, s[14:15]
	global_load_lds_dwordx4 v[140:141], off
	s_add_u32 m0, m0, 0x1000
	v_lshl_add_u64 v[140:141], v[122:123], 0, s[14:15]
	global_load_lds_dwordx4 v[140:141], off
	s_add_u32 m0, m0, 0x1000
	v_lshl_add_u64 v[140:141], v[128:129], 0, s[14:15]
	global_load_lds_dwordx4 v[140:141], off
	s_add_u32 m0, m0, 0x1000
	v_lshl_add_u64 v[140:141], v[130:131], 0, s[14:15]
	global_load_lds_dwordx4 v[140:141], off
	s_add_u32 m0, m0, 0x1000
	v_lshl_add_u64 v[140:141], v[136:137], 0, s[14:15]
	global_load_lds_dwordx4 v[140:141], off
	s_add_u32 m0, m0, 0x1000
	v_lshl_add_u64 v[140:141], v[138:139], 0, s[14:15]
	global_load_lds_dwordx4 v[140:141], off
